# v3: attention phase K/V/Q tile loads as global_load (vmcnt only) instead of flat_load; redundant 32-state pad after QK MFMAs removed
# speedup vs baseline: 1.0084x; 1.0010x over previous
.LBB0_2405:
	s_add_i32 s1, s5, s8
	s_ashr_i32 s0, s1, 3
	s_lshl_b32 s1, s1, 5
	s_lshl_b32 s10, s5, 8
	s_and_b32 s1, s1, 0xfffff800
	s_and_b32 s10, s10, 0x700
	s_or_b32 s40, s1, s10
	s_ashr_i32 s41, s40, 31
	s_and_b32 s60, s0, 7
	s_lshl_b64 s[10:11], s[40:41], 3
	s_or_b32 s1, s10, s60
	s_mul_i32 s10, s11, 0xc0
	s_mul_hi_u32 s11, s1, 0xc0
	s_add_i32 s11, s11, s10
	s_mulk_i32 s1, 0xc0
	s_add_u32 s12, s35, s1
	s_addc_u32 s13, s48, s11
	s_ashr_i32 s1, s0, 31
	s_mul_i32 s14, s0, 0x60000
	s_mul_hi_i32 s15, s0, 0x60000
	s_add_u32 s10, s49, s14
	v_mov_b32_e32 v54, v0
	s_addc_u32 s11, s50, s15
	s_lshl_b64 s[42:43], s[0:1], 19
	s_movk_i32 s0, 0xffe0
	v_ashrrev_i32_e32 v56, 1, v54
	v_bfi_b32 v2, s0, v56, v54
	v_mov_b64_e32 v[4:5], s[12:13]
	s_movk_i32 s0, 0x600
	v_mad_i64_i32 v[4:5], s[0:1], v2, s0, v[4:5]
	v_and_b32_e32 v2, 32, v54
	v_lshl_add_u64 v[4:5], v[4:5], 0, v[2:3]
	v_lshlrev_b32_e32 v2, 3, v54
	v_and_b32_e32 v19, 0x78, v2
	v_mul_hi_i32 v2, v54, s56
	global_load_dwordx4 v[116:119], v[4:5], off
	global_load_dwordx4 v[120:123], v[4:5], off offset:16
	global_load_dwordx4 v[108:111], v[4:5], off offset:64
	global_load_dwordx4 v[112:115], v[4:5], off offset:80
	global_load_dwordx4 v[100:103], v[4:5], off offset:128
	global_load_dwordx4 v[104:107], v[4:5], off offset:144
	v_lshrrev_b32_e32 v4, 31, v2
	v_ashrrev_i32_e32 v2, 1, v2
	v_ashrrev_i32_e32 v36, 4, v54
	v_add_u32_e32 v57, v2, v4
	v_add_u32_e32 v16, 32, v36
	v_mul_lo_u32 v2, v57, 12
	s_add_u32 s44, s51, s42
	v_sub_u32_e32 v18, v54, v2
	v_ashrrev_i32_e32 v37, 31, v36
	v_ashrrev_i32_e32 v17, 31, v16
	s_addc_u32 s45, s52, s43
	v_lshlrev_b64 v[48:49], 8, v[36:37]
	v_lshlrev_b64 v[6:7], 8, v[16:17]
	v_mov_b64_e32 v[12:13], s[10:11]
	v_lshlrev_b32_e32 v50, 4, v18
	v_lshl_add_u64 v[4:5], s[44:45], 0, v[48:49]
	v_lshlrev_b32_e32 v2, 1, v19
	v_lshl_add_u64 v[6:7], s[44:45], 0, v[6:7]
	v_mad_i64_i32 v[12:13], s[0:1], v57, s55, v[12:13]
	v_ashrrev_i32_e32 v51, 31, v50
	v_lshl_add_u64 v[4:5], v[4:5], 0, v[2:3]
	v_lshl_add_u64 v[6:7], v[6:7], 0, v[2:3]
	v_lshl_add_u64 v[12:13], v[12:13], 0, v[50:51]
	global_load_dwordx4 v[8:11], v[4:5], off
	s_nop 0
	global_load_dwordx4 v[4:7], v[6:7], off
	v_add_u32_e32 v17, 0x200, v54
	global_load_dwordx4 v[12:15], v[12:13], off
	v_mul_hi_i32 v20, v17, s56
	v_lshrrev_b32_e32 v21, 31, v20
	v_ashrrev_i32_e32 v20, 1, v20
	v_add_u32_e32 v55, v20, v21
	v_mul_lo_u32 v20, v55, 12
	v_sub_u32_e32 v17, v17, v20
	v_lshlrev_b32_e32 v52, 4, v17
	v_cmp_gt_i32_e64 s[12:13], s6, v54
	v_mov_b32_e32 v124, v3
	v_mov_b32_e32 v125, v3
	v_mov_b32_e32 v126, v3
	v_mov_b32_e32 v127, v3
	v_ashrrev_i32_e32 v53, 31, v52
	s_and_saveexec_b64 s[46:47], s[12:13]
	s_cbranch_execz .LBB0_2407
	v_mov_b64_e32 v[20:21], s[10:11]
	v_mad_i64_i32 v[20:21], s[0:1], v55, s55, v[20:21]
	v_lshl_add_u64 v[20:21], v[20:21], 0, v[52:53]
	global_load_dwordx4 v[124:127], v[20:21], off
.LBB0_2407:
	s_or_b64 exec, exec, s[46:47]
	v_and_b32_e32 v20, 0xfffff0, v36
	v_lshlrev_b32_e32 v21, 1, v36
	v_and_b32_e32 v23, 0xfffff0, v16
	v_lshlrev_b32_e32 v16, 1, v16
	v_and_or_b32 v20, v21, 8, v20
	v_and_or_b32 v16, v16, 8, v23
	v_lshrrev_b32_e32 v21, 1, v36
	v_lshrrev_b32_e32 v20, 1, v20
	v_lshrrev_b32_e32 v19, 5, v19
	v_and_b32_e32 v22, 3, v36
	v_lshrrev_b32_e32 v16, 1, v16
	v_or_b32_e32 v20, v20, v19
	v_and_or_b32 v21, v21, 4, v22
	v_or_b32_e32 v16, v16, v19
	v_lshlrev_b32_e32 v20, 9, v20
	v_lshlrev_b32_e32 v21, 6, v21
	v_and_b32_e32 v22, 48, v2
	v_lshlrev_b32_e32 v16, 9, v16
	v_or3_b32 v20, v20, v21, v22
	v_or3_b32 v16, v16, v21, v22
	v_add_u32_e32 v179, 0, v20
	v_add_u32_e32 v180, 0, v16
	s_waitcnt vmcnt(0)
	s_waitcnt vmcnt(0) lgkmcnt(0)
	ds_write_b128 v179, v[8:11]
	ds_write_b128 v180, v[4:7]
	v_lshrrev_b32_e32 v5, 2, v57
	v_mul_lo_u32 v4, v57, s55
	v_bitop3_b32 v5, v5, v18, 3 bitop3:0x6c
	v_lshl_add_u32 v4, v5, 4, v4
	v_add_u32_e32 v183, 0, v4
	v_lshrrev_b32_e32 v4, 2, v55
	v_mul_lo_u32 v58, v55, s55
	v_bitop3_b32 v59, v4, v17, 3 bitop3:0x6c
	ds_write_b128 v183, v[12:15] offset:32768
	s_and_saveexec_b64 s[46:47], s[12:13]
	v_lshlrev_b32_e32 v4, 4, v59
	v_add3_u32 v4, 0, v58, v4
	ds_write_b128 v4, v[124:127] offset:32768
	s_or_b64 exec, exec, s[46:47]
	v_bfe_u32 v173, v54, 5, 1
	v_lshrrev_b32_e32 v4, 2, v54
	v_lshlrev_b32_e32 v7, 1, v173
	v_and_b32_e32 v172, 31, v54
	v_bfe_u32 v5, v54, 2, 2
	v_mov_b32_e32 v6, s57
	v_bitop3_b32 v4, v7, v4, 3 bitop3:0x78
	v_mad_u32_u24 v6, v172, s55, v6
	v_lshlrev_b32_e32 v4, 4, v4
	v_bitop3_b32 v5, v7, v5, 1 bitop3:0x36
	v_lshlrev_b32_e32 v5, 4, v5
	s_waitcnt lgkmcnt(0)
	s_barrier
	s_nop 1
	v_add_u32_e32 v181, v4, v6
	v_add_u32_e32 v182, v5, v6
	ds_read_b128 v[38:41], v181
	ds_read_b128 v[60:63], v181 offset:6144
	ds_read_b128 v[42:45], v182
	ds_read_b128 v[64:67], v182 offset:6144
	v_mov_b64_e32 v[4:5], s[16:17]
	v_mov_b64_e32 v[18:19], s[30:31]
	v_mov_b64_e32 v[6:7], s[18:19]
	v_mov_b64_e32 v[8:9], s[20:21]
	v_mov_b64_e32 v[10:11], s[22:23]
	v_mov_b64_e32 v[12:13], s[24:25]
	v_mov_b64_e32 v[14:15], s[26:27]
	v_mov_b64_e32 v[16:17], s[28:29]
	v_mov_b64_e32 v[34:35], v[18:19]
	v_mov_b64_e32 v[32:33], v[16:17]
	v_mov_b64_e32 v[30:31], v[14:15]
	v_mov_b64_e32 v[28:29], v[12:13]
	v_mov_b64_e32 v[26:27], v[10:11]
	v_mov_b64_e32 v[24:25], v[8:9]
	v_mov_b64_e32 v[22:23], v[6:7]
	v_mov_b64_e32 v[20:21], v[4:5]
	s_waitcnt lgkmcnt(1)
	v_mfma_scale_f32_32x32x64_f8f6f4 v[20:35], v[38:45], v[116:123], v[20:35], v170, v170 op_sel_hi:[0,0,0]
	s_waitcnt lgkmcnt(0)
	v_mfma_scale_f32_32x32x64_f8f6f4 v[4:19], v[60:67], v[116:123], v[4:19], v170, v170 op_sel_hi:[0,0,0]
	ds_read_b128 v[38:41], v181 offset:64
	ds_read_b128 v[60:63], v181 offset:6208
	ds_read_b128 v[42:45], v182 offset:64
	ds_read_b128 v[64:67], v182 offset:6208
	s_waitcnt lgkmcnt(1)
	v_mfma_scale_f32_32x32x64_f8f6f4 v[20:35], v[38:45], v[108:115], v[20:35], v170, v170 op_sel_hi:[0,0,0]
	s_waitcnt lgkmcnt(0)
	v_mfma_scale_f32_32x32x64_f8f6f4 v[4:19], v[60:67], v[108:115], v[4:19], v170, v170 op_sel_hi:[0,0,0]
	ds_read_b128 v[38:41], v181 offset:128
	ds_read_b128 v[60:63], v181 offset:6272
	ds_read_b128 v[42:45], v182 offset:128
	ds_read_b128 v[64:67], v182 offset:6272
	v_lshlrev_b64 v[36:37], 8, v[36:37]
	v_lshl_add_u64 v[36:37], s[44:45], 0, v[36:37]
	v_lshl_add_u64 v[36:37], v[36:37], 0, v[2:3]
	s_waitcnt lgkmcnt(1)
	v_mfma_scale_f32_32x32x64_f8f6f4 v[20:35], v[38:45], v[100:107], v[20:35], v170, v170 op_sel_hi:[0,0,0]
	v_add_co_u32_e32 v38, vcc, s59, v36
	v_add_u32_e32 v2, 64, v57
	s_nop 0
	v_addc_co_u32_e32 v39, vcc, 0, v37, vcc
	v_mov_b64_e32 v[44:45], s[10:11]
	v_add_co_u32_e32 v40, vcc, 0x6000, v36
	v_mad_i64_i32 v[44:45], s[0:1], v2, s55, v[44:45]
	s_waitcnt lgkmcnt(0)
	v_mfma_scale_f32_32x32x64_f8f6f4 v[4:19], v[60:67], v[100:107], v[4:19], v170, v170 op_sel_hi:[0,0,0]
	v_addc_co_u32_e32 v41, vcc, 0, v37, vcc
	v_lshl_add_u64 v[44:45], v[44:45], 0, v[50:51]
	s_nop 15
	s_nop 15
	global_load_dwordx4 v[36:39], v[38:39], off
	s_nop 0
	global_load_dwordx4 v[40:43], v[40:41], off
	v_max_f32_e32 v2, v21, v21
	global_load_dwordx4 v[44:47], v[44:45], off
	v_max_f32_e32 v60, v20, v20
	v_max_f32_e32 v2, v60, v2
	v_max3_f32 v2, v2, v22, v23
	v_max3_f32 v2, v2, v24, v25
	v_max3_f32 v2, v2, v26, v27
	v_max3_f32 v2, v2, v28, v29
	v_max3_f32 v2, v2, v30, v31
	v_max3_f32 v2, v2, v32, v33
	v_max3_f32 v2, v2, v34, v35
	v_max3_f32 v2, v2, v4, v5
	v_max3_f32 v2, v2, v6, v7
	v_max3_f32 v2, v2, v8, v9
	v_max3_f32 v2, v2, v10, v11
	v_max3_f32 v2, v2, v12, v13
	v_max3_f32 v2, v2, v14, v15
	v_max3_f32 v2, v2, v16, v17
	v_max3_f32 v2, v2, v18, v19
	v_mov_b32_e32 v60, v2
	s_nop 1
	v_permlane32_swap_b32_e32 v2, v60
	v_max_f32_e32 v60, v60, v60
	v_max_f32_e32 v2, v2, v2
	v_max_f32_e32 v2, v2, v60
	v_add_f32_e32 v60, 0x7149f2ca, v2
	v_cmp_ge_f32_e32 vcc, s58, v60
	s_cmp_eq_u64 vcc, exec
	s_cselect_b64 vcc, -1, 0
	s_and_saveexec_b64 s[44:45], s[12:13]
	s_cbranch_execz .LBB0_2411
	v_add_u32_e32 v62, 64, v55
	v_mov_b64_e32 v[60:61], s[10:11]
	v_mad_i64_i32 v[60:61], s[0:1], v62, s55, v[60:61]
	v_lshl_add_u64 v[60:61], v[60:61], 0, v[52:53]
	global_load_dwordx4 v[124:127], v[60:61], off

.LBB0_2414:
	s_nop 1
	ds_read_b128 v[188:191], v181 offset:12288
	ds_read_b128 v[196:199], v181 offset:18432
	ds_read_b128 v[192:195], v182 offset:12288
	ds_read_b128 v[200:203], v182 offset:18432
	v_add_f32_e32 v2, 0, v150
	v_mov_b64_e32 v[82:83], s[30:31]
	v_add_f32_e32 v2, v151, v2
	v_mov_b64_e32 v[80:81], s[28:29]
	v_mov_b64_e32 v[78:79], s[26:27]
	v_mov_b64_e32 v[76:77], s[24:25]
	v_mov_b64_e32 v[74:75], s[22:23]
	v_mov_b64_e32 v[72:73], s[20:21]
	v_mov_b64_e32 v[70:71], s[18:19]
	v_mov_b64_e32 v[68:69], s[16:17]
	v_mov_b64_e32 v[98:99], v[82:83]
	v_add_f32_e32 v2, v152, v2
	v_mov_b64_e32 v[96:97], v[80:81]
	v_mov_b64_e32 v[94:95], v[78:79]
	v_mov_b64_e32 v[92:93], v[76:77]
	v_mov_b64_e32 v[90:91], v[74:75]
	v_mov_b64_e32 v[88:89], v[72:73]
	v_mov_b64_e32 v[86:87], v[70:71]
	v_mov_b64_e32 v[84:85], v[68:69]
	v_add_f32_e32 v2, v153, v2
	s_waitcnt lgkmcnt(1)
	v_mfma_scale_f32_32x32x64_f8f6f4 v[84:99], v[188:195], v[116:123], v[84:99], v170, v170 op_sel_hi:[0,0,0]
	s_waitcnt lgkmcnt(0)
	v_mfma_scale_f32_32x32x64_f8f6f4 v[68:83], v[196:203], v[116:123], v[68:83], v170, v170 op_sel_hi:[0,0,0]
	ds_read_b128 v[188:191], v181 offset:12352
	ds_read_b128 v[196:199], v181 offset:18496
	ds_read_b128 v[192:195], v182 offset:12352
	ds_read_b128 v[200:203], v182 offset:18496
	v_add_f32_e32 v2, v154, v2
	v_add_f32_e32 v2, v165, v2
	v_add_f32_e32 v2, v166, v2
	v_add_f32_e32 v2, v168, v2
	v_add_f32_e32 v2, v145, v2
	s_waitcnt lgkmcnt(1)
	v_mfma_scale_f32_32x32x64_f8f6f4 v[84:99], v[188:195], v[108:115], v[84:99], v170, v170 op_sel_hi:[0,0,0]
	s_waitcnt lgkmcnt(0)
	v_mfma_scale_f32_32x32x64_f8f6f4 v[68:83], v[196:203], v[108:115], v[68:83], v170, v170 op_sel_hi:[0,0,0]
	ds_read_b128 v[188:191], v181 offset:12416
	ds_read_b128 v[196:199], v181 offset:18560
	ds_read_b128 v[192:195], v182 offset:12416
	ds_read_b128 v[200:203], v182 offset:18560
	v_add_f32_e32 v2, v146, v2
	v_add_f32_e32 v2, v147, v2
	v_add_f32_e32 v2, v148, v2
	v_exp_f32_e32 v169, v140
	v_add_f32_e32 v2, v149, v2
	s_waitcnt lgkmcnt(1)
	v_mfma_scale_f32_32x32x64_f8f6f4 v[84:99], v[188:195], v[100:107], v[84:99], v170, v170 op_sel_hi:[0,0,0]
	v_exp_f32_e32 v188, v141
	v_add_f32_e32 v2, v155, v2
	v_exp_f32_e32 v136, v136
	v_add_f32_e32 v2, v164, v2
	v_exp_f32_e32 v137, v137
	v_add_f32_e32 v2, v167, v2
	v_exp_f32_e32 v134, v134
	v_add_f32_e32 v2, v169, v2
	v_exp_f32_e32 v135, v135
	v_add_f32_e32 v2, v188, v2
	v_exp_f32_e32 v130, v130
	v_add_f32_e32 v2, v136, v2
	v_exp_f32_e32 v131, v131
	v_add_f32_e32 v2, v137, v2
	v_exp_f32_e32 v128, v128
	v_add_f32_e32 v2, v134, v2
	v_exp_f32_e32 v129, v129
	v_add_f32_e32 v2, v135, v2
	v_exp_f32_e32 v189, v142
	v_add_f32_e32 v2, v130, v2
	v_exp_f32_e32 v190, v143
	v_add_f32_e32 v2, v131, v2
	v_exp_f32_e32 v138, v138
	v_add_f32_e32 v2, v128, v2
	v_exp_f32_e32 v139, v139
	v_add_f32_e32 v2, v129, v2
	v_exp_f32_e32 v132, v132
	v_add_f32_e32 v2, v189, v2
	v_exp_f32_e32 v133, v133
	v_add_f32_e32 v2, v190, v2
	v_add_f32_e32 v2, v138, v2
	v_add_f32_e32 v2, v139, v2
	v_add_f32_e32 v2, v132, v2
	v_add_f32_e32 v2, v133, v2
	v_mov_b32_e32 v187, v2
	v_cvt_pk_bf16_f32 v140, v150, v151
	v_cvt_pk_bf16_f32 v141, v152, v153
	v_cvt_pk_bf16_f32 v142, v154, v165
	v_cvt_pk_bf16_f32 v143, v166, v168
	v_cvt_pk_bf16_f32 v144, v145, v146
	v_cvt_pk_bf16_f32 v145, v147, v148
	v_cvt_pk_bf16_f32 v146, v149, v155
	v_cvt_pk_bf16_f32 v147, v164, v167
	v_cvt_pk_bf16_f32 v148, v169, v188
	v_cvt_pk_bf16_f32 v149, v136, v137
	v_cvt_pk_bf16_f32 v150, v134, v135
	v_cvt_pk_bf16_f32 v151, v130, v131
	v_cvt_pk_bf16_f32 v152, v128, v129
	v_cvt_pk_bf16_f32 v153, v189, v190
	v_cvt_pk_bf16_f32 v154, v138, v139
	v_cvt_pk_bf16_f32 v155, v132, v133
	s_waitcnt lgkmcnt(0)
	v_mfma_scale_f32_32x32x64_f8f6f4 v[68:83], v[196:203], v[100:107], v[68:83], v170, v170 op_sel_hi:[0,0,0]
	v_permlane32_swap_b32_e32 v2, v187
	v_permlane32_swap_b32_e32 v140, v142
	v_permlane32_swap_b32_e32 v141, v143
	v_permlane32_swap_b32_e32 v144, v146
	v_permlane32_swap_b32_e32 v145, v147
	v_permlane32_swap_b32_e32 v148, v150
	v_permlane32_swap_b32_e32 v149, v151
	v_permlane32_swap_b32_e32 v152, v154
	v_permlane32_swap_b32_e32 v153, v155
	v_lshl_add_u64 v[166:167], s[38:39], 0, v[162:163]
	s_mov_b32 s0, 0x2a108000
	v_add_co_u32_e32 v128, vcc, s0, v166
	v_lshl_add_u64 v[168:169], s[38:39], 0, v[160:161]
	s_nop 0
	v_addc_co_u32_e32 v129, vcc, 0, v167, vcc
	v_add_co_u32_e32 v132, vcc, 0x2a10a000, v166
	v_lshl_add_u64 v[164:165], s[38:39], 0, v[158:159]
	s_nop 0
	v_addc_co_u32_e32 v133, vcc, 0, v167, vcc
	v_add_co_u32_e32 v136, vcc, 0x1e106000, v168
	global_load_dwordx4 v[128:131], v[128:129], off
	s_nop 0
	global_load_dwordx4 v[132:135], v[132:133], off
	v_addc_co_u32_e32 v137, vcc, 0, v169, vcc
	global_load_dwordx4 v[136:139], v[136:137], off
	s_and_saveexec_b64 s[14:15], s[12:13]
	s_cbranch_execz .LBB0_2416
	v_add_co_u32_e32 v124, vcc, 0x1e106000, v164
	s_nop 1
	v_addc_co_u32_e32 v125, vcc, 0, v165, vcc
	global_load_dwordx4 v[124:127], v[124:125], off

.LBB0_2422:
	v_cndmask_b32_e64 v185, v128, v185, s[14:15]
	v_mul_f32_e32 v138, 0xbdd53b94, v185
	v_fmamk_f32 v84, v84, 0x3dd53b94, v138
	v_fmamk_f32 v85, v85, 0x3dd53b94, v138
	v_fmamk_f32 v86, v86, 0x3dd53b94, v138
	v_fmamk_f32 v87, v87, 0x3dd53b94, v138
	v_fmamk_f32 v88, v88, 0x3dd53b94, v138
	v_fmamk_f32 v89, v89, 0x3dd53b94, v138
	v_fmamk_f32 v90, v90, 0x3dd53b94, v138
	v_fmamk_f32 v91, v91, 0x3dd53b94, v138
	v_fmamk_f32 v92, v92, 0x3dd53b94, v138
	v_fmamk_f32 v93, v93, 0x3dd53b94, v138
	v_fmamk_f32 v94, v94, 0x3dd53b94, v138
	v_fmamk_f32 v95, v95, 0x3dd53b94, v138
	v_fmamk_f32 v96, v96, 0x3dd53b94, v138
	v_fmamk_f32 v97, v97, 0x3dd53b94, v138
	v_fmamk_f32 v98, v98, 0x3dd53b94, v138
	v_fmamk_f32 v99, v99, 0x3dd53b94, v138
	v_exp_f32_e32 v131, v84
	v_exp_f32_e32 v134, v85
	v_exp_f32_e32 v135, v86
	v_exp_f32_e32 v139, v87
	v_exp_f32_e32 v142, v88
	v_exp_f32_e32 v143, v89
	v_exp_f32_e32 v144, v90
	v_exp_f32_e32 v145, v91
	v_exp_f32_e32 v128, v92
	v_exp_f32_e32 v129, v93
	v_exp_f32_e32 v130, v94
	v_exp_f32_e32 v132, v95
	v_exp_f32_e32 v133, v96
	v_exp_f32_e32 v136, v97
	v_exp_f32_e32 v137, v98
	v_exp_f32_e32 v147, v99
	v_fmamk_f32 v140, v68, 0x3dd53b94, v138
	v_fmamk_f32 v141, v69, 0x3dd53b94, v138
	v_fmamk_f32 v146, v70, 0x3dd53b94, v138
	v_fmamk_f32 v148, v71, 0x3dd53b94, v138
	v_fmamk_f32 v149, v72, 0x3dd53b94, v138
	v_fmamk_f32 v150, v73, 0x3dd53b94, v138
	v_fmamk_f32 v151, v74, 0x3dd53b94, v138
	v_fmamk_f32 v152, v75, 0x3dd53b94, v138
	v_fmamk_f32 v153, v76, 0x3dd53b94, v138
	v_fmamk_f32 v154, v77, 0x3dd53b94, v138
	v_fmamk_f32 v155, v78, 0x3dd53b94, v138
	v_fmamk_f32 v189, v79, 0x3dd53b94, v138
	v_fmamk_f32 v190, v80, 0x3dd53b94, v138
	v_fmamk_f32 v191, v81, 0x3dd53b94, v138
	v_fmamk_f32 v192, v82, 0x3dd53b94, v138
	v_fmac_f32_e32 v138, 0x3dd53b94, v83
	s_waitcnt lgkmcnt(0)
	s_barrier
	s_nop 1
	ds_read_b128 v[194:197], v181
	ds_read_b128 v[202:205], v181 offset:6144
	ds_read_b128 v[198:201], v182
	ds_read_b128 v[206:209], v182 offset:6144
	v_exp_f32_e32 v193, v140
	v_add_f32_e32 v140, 0, v131
	v_mov_b64_e32 v[82:83], s[30:31]
	v_add_f32_e32 v140, v134, v140
	v_mov_b64_e32 v[80:81], s[28:29]
	v_mov_b64_e32 v[78:79], s[26:27]
	v_mov_b64_e32 v[76:77], s[24:25]
	v_mov_b64_e32 v[74:75], s[22:23]
	v_mov_b64_e32 v[72:73], s[20:21]
	v_mov_b64_e32 v[70:71], s[18:19]
	v_mov_b64_e32 v[68:69], s[16:17]
	v_mov_b64_e32 v[98:99], v[82:83]
	v_add_f32_e32 v140, v135, v140
	v_mov_b64_e32 v[96:97], v[80:81]
	v_mov_b64_e32 v[94:95], v[78:79]
	v_mov_b64_e32 v[92:93], v[76:77]
	v_mov_b64_e32 v[90:91], v[74:75]
	v_mov_b64_e32 v[88:89], v[72:73]
	v_mov_b64_e32 v[86:87], v[70:71]
	v_mov_b64_e32 v[84:85], v[68:69]
	v_add_f32_e32 v140, v139, v140
	s_waitcnt lgkmcnt(1)
	v_mfma_scale_f32_32x32x64_f8f6f4 v[84:99], v[194:201], v[116:123], v[84:99], v170, v170 op_sel_hi:[0,0,0]
	s_waitcnt lgkmcnt(0)
	v_mfma_scale_f32_32x32x64_f8f6f4 v[68:83], v[202:209], v[116:123], v[68:83], v170, v170 op_sel_hi:[0,0,0]
	ds_read_b128 v[194:197], v181 offset:64
	ds_read_b128 v[202:205], v181 offset:6208
	ds_read_b128 v[198:201], v182 offset:64
	ds_read_b128 v[206:209], v182 offset:6208
	v_add_f32_e32 v140, v142, v140
	v_add_f32_e32 v140, v143, v140
	v_add_f32_e32 v140, v144, v140
	v_add_f32_e32 v140, v145, v140
	v_add_f32_e32 v140, v128, v140
	s_waitcnt lgkmcnt(1)
	v_mfma_scale_f32_32x32x64_f8f6f4 v[84:99], v[194:201], v[108:115], v[84:99], v170, v170 op_sel_hi:[0,0,0]
	s_waitcnt lgkmcnt(0)
	v_mfma_scale_f32_32x32x64_f8f6f4 v[68:83], v[202:209], v[108:115], v[68:83], v170, v170 op_sel_hi:[0,0,0]
	ds_read_b128 v[194:197], v181 offset:128
	ds_read_b128 v[202:205], v181 offset:6272
	ds_read_b128 v[198:201], v182 offset:128
	ds_read_b128 v[206:209], v182 offset:6272
	v_add_f32_e32 v140, v129, v140
	v_add_f32_e32 v140, v130, v140
	v_add_f32_e32 v140, v132, v140
	v_add_f32_e32 v140, v133, v140
	s_waitcnt lgkmcnt(1)
	v_mfma_scale_f32_32x32x64_f8f6f4 v[84:99], v[194:201], v[100:107], v[84:99], v170, v170 op_sel_hi:[0,0,0]
	v_exp_f32_e32 v194, v141
	v_add_f32_e32 v140, v136, v140
	v_exp_f32_e32 v195, v146
	v_add_f32_e32 v140, v137, v140
	v_exp_f32_e32 v196, v148
	v_add_f32_e32 v140, v147, v140
	v_exp_f32_e32 v197, v149
	v_add_f32_e32 v140, v193, v140
	v_exp_f32_e32 v150, v150
	v_add_f32_e32 v140, v194, v140
	v_exp_f32_e32 v151, v151
	v_add_f32_e32 v140, v195, v140
	v_exp_f32_e32 v152, v152
	v_add_f32_e32 v140, v196, v140
	v_exp_f32_e32 v153, v153
	v_add_f32_e32 v140, v197, v140
	v_exp_f32_e32 v154, v154
	v_add_f32_e32 v140, v150, v140
	v_exp_f32_e32 v155, v155
	v_add_f32_e32 v140, v151, v140
	v_exp_f32_e32 v198, v189
	v_add_f32_e32 v140, v152, v140
	v_exp_f32_e32 v199, v190
	v_add_f32_e32 v140, v153, v140
	v_exp_f32_e32 v191, v191
	v_add_f32_e32 v140, v154, v140
	v_exp_f32_e32 v192, v192
	v_add_f32_e32 v140, v155, v140
	v_exp_f32_e32 v138, v138
	v_add_f32_e32 v140, v198, v140
	v_add_f32_e32 v140, v199, v140
	v_add_f32_e32 v140, v191, v140
	v_add_f32_e32 v140, v192, v140
	v_add_f32_e32 v189, v138, v140
	v_mov_b32_e32 v190, v189
	v_cvt_pk_bf16_f32 v140, v131, v134
	v_cvt_pk_bf16_f32 v141, v135, v139
	v_cvt_pk_bf16_f32 v142, v142, v143
	v_cvt_pk_bf16_f32 v143, v144, v145
	v_cvt_pk_bf16_f32 v144, v128, v129
	v_cvt_pk_bf16_f32 v145, v130, v132
	v_cvt_pk_bf16_f32 v146, v133, v136
	v_cvt_pk_bf16_f32 v147, v137, v147
	v_cvt_pk_bf16_f32 v148, v193, v194
	v_cvt_pk_bf16_f32 v149, v195, v196
	v_cvt_pk_bf16_f32 v150, v197, v150
	v_cvt_pk_bf16_f32 v151, v151, v152
	v_cvt_pk_bf16_f32 v152, v153, v154
	v_cvt_pk_bf16_f32 v153, v155, v198
	v_cvt_pk_bf16_f32 v154, v199, v191
	v_cvt_pk_bf16_f32 v155, v192, v138
	s_waitcnt lgkmcnt(0)
	v_mfma_scale_f32_32x32x64_f8f6f4 v[68:83], v[202:209], v[100:107], v[68:83], v170, v170 op_sel_hi:[0,0,0]
	v_permlane32_swap_b32_e32 v189, v190
	v_permlane32_swap_b32_e32 v140, v142
	v_permlane32_swap_b32_e32 v141, v143
	v_permlane32_swap_b32_e32 v144, v146
	v_permlane32_swap_b32_e32 v145, v147
	v_permlane32_swap_b32_e32 v148, v150
	v_permlane32_swap_b32_e32 v149, v151
	v_permlane32_swap_b32_e32 v152, v154
	v_permlane32_swap_b32_e32 v153, v155
	s_mov_b32 s0, 0x2a10c000
	v_add_co_u32_e32 v128, vcc, s0, v166
	s_nop 1
	v_addc_co_u32_e32 v129, vcc, 0, v167, vcc
	v_add_co_u32_e32 v132, vcc, 0x2a10e000, v166
	s_nop 1
	v_addc_co_u32_e32 v133, vcc, 0, v167, vcc
	v_add_co_u32_e32 v136, vcc, 0x1e109000, v168
	global_load_dwordx4 v[128:131], v[128:129], off
	s_nop 0
	global_load_dwordx4 v[132:135], v[132:133], off
	v_addc_co_u32_e32 v137, vcc, 0, v169, vcc
	global_load_dwordx4 v[136:139], v[136:137], off
	s_and_saveexec_b64 s[14:15], s[12:13]
	s_cbranch_execz .LBB0_2424
	v_add_co_u32_e32 v124, vcc, 0x1e109000, v164
	s_nop 1
	v_addc_co_u32_e32 v125, vcc, 0, v165, vcc
	global_load_dwordx4 v[124:127], v[124:125], off
